# MoBA phase: static s_setprio 1 for waves 4-7 (lockstep SIMD partners skew so one wave's softmax VALU overlaps the other's MFMA)
# baseline (speedup 1.0000x reference)
.LBB0_869:
	v_lshrrev_b32_e32 v2, 8, v186
	s_nop 1
	v_readfirstlane_b32 s98, v2
	s_nop 1
	s_cmp_eq_u32 s98, 0
	s_cbranch_scc1 .Lmoba_prio_skip
	s_setprio 1

.LBB0_939:
	s_setprio 0
	v_readlane_b32 s18, v251, 63
	v_readlane_b32 s19, v250, 0
	v_readlane_b32 s86, v251, 51
	s_and_b64 vcc, exec, s[18:19]
	v_readlane_b32 s87, v251, 52
	s_cbranch_vccz .LBB0_993
	s_waitcnt vmcnt(0)
	s_barrier
	s_mov_b64 s[0:1], exec
	v_readlane_b32 s2, v252, 28
	v_readlane_b32 s3, v252, 29
	s_and_b64 s[2:3], s[0:1], s[2:3]
	s_mov_b64 exec, s[2:3]
	s_cbranch_execz .LBB0_992
	s_add_i32 s2, 0, 0x27020
	v_mov_b32_e32 v2, s2
	s_waitcnt vmcnt(0) expcnt(0) lgkmcnt(0)
	ds_read_b32 v4, v2
	s_add_i32 s2, 0, 0x27024
	v_mov_b32_e32 v2, s2
	ds_read_b32 v2, v2
	s_waitcnt lgkmcnt(1)
	v_cmp_ne_u32_e32 vcc, 0, v4
	s_cbranch_vccnz .LBB0_956
	v_readlane_b32 s4, v252, 0
	v_readlane_b32 s5, v252, 1
	s_load_dwordx2 s[2:3], s[4:5], 0x4
	v_readlane_b32 s4, v252, 2
	v_mov_b32_e32 v18, 0
	v_readlane_b32 s5, v252, 3
	s_waitcnt lgkmcnt(0)
	s_mul_i32 s2, s2, s4
	s_mul_i32 s2, s2, s3
	s_mov_b32 s3, 1
	s_branch .LBB0_944
